# v21
# speedup vs baseline: 1.0109x; 1.0108x over previous
.LBB0_624:
	s_or_b64 exec, exec, s[6:7]
	s_cmpk_gt_i32 s52, 0x323f
	s_cbranch_scc1 .LBB0_681
	s_waitcnt lgkmcnt(0)
	s_add_u32 s16, s8, 0x2fb27800
	s_addc_u32 s17, s9, 0
	s_add_u32 s20, s8, 0x1c80000
	s_addc_u32 s21, s9, 0
	s_add_u32 s22, s8, 0x1480000
	s_addc_u32 s23, s9, 0
	s_add_u32 s56, s8, 0xe80000
	s_addc_u32 s65, s9, 0
	s_lshl_b32 s68, s52, 6
	s_cmp_lg_u32 s25, 0x100
	s_cbranch_scc1 .LBB0_628
	s_load_dwordx2 s[10:11], s[0:1], 0x40
	v_and_b32_e32 v72, 63, v208
	v_lshrrev_b32_e32 v73, 6, v208
	v_mul_u32_u24_e32 v82, 65, v73
	v_add_lshl_u32 v82, v82, v72, 2
	v_lshrrev_b32_e32 v83, 3, v208
	v_and_b32_e32 v84, 7, v208
	v_lshlrev_b32_e32 v84, 3, v84
	v_mul_u32_u24_e32 v85, 0x104, v84
	v_lshl_add_u32 v85, v83, 2, v85
	v_add_u32_e32 v87, 0x4200, v82
	v_add_u32_e32 v88, 0x4200, v85
	v_add_u32_e32 v89, 0x410, v85
	v_add_u32_e32 v90, 0x410, v88
	v_lshlrev_b32_e32 v91, 11, v83
	v_lshl_add_u32 v91, v84, 1, v91
	v_mul_u32_u24_e32 v94, 0x7040, v73
	s_waitcnt lgkmcnt(0)
	s_mov_b32 s34, s52
	s_cmpk_gt_i32 s34, 0x73f
	s_cbranch_scc1 .Lp0w_issued
	s_lshr_b32 s30, s34, 4
	s_and_b32 s6, s34, 15
	s_lshl_b32 s7, s30, 6
	s_mov_b32 s76, 64
	s_cmp_lt_u32 s30, 48
	s_cselect_b32 s77, 0, 16
	s_add_u32 s7, s7, s77
	s_cmp_lt_u32 s30, 0x70
	s_cselect_b32 s7, s7, 0xc00
	s_cselect_b32 s76, s76, 16
	s_cmp_lt_u32 s30, 0x71
	s_cselect_b32 s7, s7, 0
	s_cselect_b32 s76, s76, 0
	s_mul_i32 s77, s6, 0x1c1000
	s_lshl_b32 s7, s7, 2
	s_add_u32 s77, s77, s7
	s_add_u32 s12, s10, s77
	s_addc_u32 s13, s11, 0
	v_cmp_gt_u32_e32 vcc, s76, v72
	s_nop 1
	v_cndmask_b32_e32 v92, 0, v72, vcc
	v_lshl_add_u32 v95, v92, 2, v94
	global_load_dword v108, v95, s[12:13]
	v_add_u32_e32 v93, 0x38200, v95
	global_load_dword v109, v93, s[12:13]
	v_add_u32_e32 v93, 0x70400, v95
	global_load_dword v110, v93, s[12:13]
	v_add_u32_e32 v93, 0xa8600, v95
	global_load_dword v111, v93, s[12:13]
	v_add_u32_e32 v93, 0xe0800, v95
	global_load_dword v112, v93, s[12:13]
	v_add_u32_e32 v93, 0x118a00, v95
	global_load_dword v113, v93, s[12:13]
	v_add_u32_e32 v93, 0x150c00, v95
	global_load_dword v114, v93, s[12:13]
	v_add_u32_e32 v93, 0x188e00, v95
	global_load_dword v115, v93, s[12:13]
	s_add_i32 s34, s34, s25
	s_cmpk_gt_i32 s34, 0x73f
	s_cbranch_scc1 .Lp0w_issued
	s_lshr_b32 s30, s34, 4
	s_and_b32 s6, s34, 15
	s_lshl_b32 s7, s30, 6
	s_mov_b32 s76, 64
	s_cmp_lt_u32 s30, 48
	s_cselect_b32 s77, 0, 16
	s_add_u32 s7, s7, s77
	s_cmp_lt_u32 s30, 0x70
	s_cselect_b32 s7, s7, 0xc00
	s_cselect_b32 s76, s76, 16
	s_cmp_lt_u32 s30, 0x71
	s_cselect_b32 s7, s7, 0
	s_cselect_b32 s76, s76, 0
	s_mul_i32 s77, s6, 0x1c1000
	s_lshl_b32 s7, s7, 2
	s_add_u32 s77, s77, s7
	s_add_u32 s12, s10, s77
	s_addc_u32 s13, s11, 0
	v_cmp_gt_u32_e32 vcc, s76, v72
	s_nop 1
	v_cndmask_b32_e32 v92, 0, v72, vcc
	v_lshl_add_u32 v95, v92, 2, v94
	global_load_dword v116, v95, s[12:13]
	v_add_u32_e32 v93, 0x38200, v95
	global_load_dword v117, v93, s[12:13]
	v_add_u32_e32 v93, 0x70400, v95
	global_load_dword v118, v93, s[12:13]
	v_add_u32_e32 v93, 0xa8600, v95
	global_load_dword v119, v93, s[12:13]
	v_add_u32_e32 v93, 0xe0800, v95
	global_load_dword v120, v93, s[12:13]
	v_add_u32_e32 v93, 0x118a00, v95
	global_load_dword v121, v93, s[12:13]
	v_add_u32_e32 v93, 0x150c00, v95
	global_load_dword v122, v93, s[12:13]
	v_add_u32_e32 v93, 0x188e00, v95
	global_load_dword v123, v93, s[12:13]
	s_add_i32 s34, s34, s25
	s_cmpk_gt_i32 s34, 0x73f
	s_cbranch_scc1 .Lp0w_issued
	s_lshr_b32 s30, s34, 4
	s_and_b32 s6, s34, 15
	s_lshl_b32 s7, s30, 6
	s_mov_b32 s76, 64
	s_cmp_lt_u32 s30, 48
	s_cselect_b32 s77, 0, 16
	s_add_u32 s7, s7, s77
	s_cmp_lt_u32 s30, 0x70
	s_cselect_b32 s7, s7, 0xc00
	s_cselect_b32 s76, s76, 16
	s_cmp_lt_u32 s30, 0x71
	s_cselect_b32 s7, s7, 0
	s_cselect_b32 s76, s76, 0
	s_mul_i32 s77, s6, 0x1c1000
	s_lshl_b32 s7, s7, 2
	s_add_u32 s77, s77, s7
	s_add_u32 s12, s10, s77
	s_addc_u32 s13, s11, 0
	v_cmp_gt_u32_e32 vcc, s76, v72
	s_nop 1
	v_cndmask_b32_e32 v92, 0, v72, vcc
	v_lshl_add_u32 v95, v92, 2, v94
	global_load_dword v124, v95, s[12:13]
	v_add_u32_e32 v93, 0x38200, v95
	global_load_dword v125, v93, s[12:13]
	v_add_u32_e32 v93, 0x70400, v95
	global_load_dword v126, v93, s[12:13]
	v_add_u32_e32 v93, 0xa8600, v95
	global_load_dword v127, v93, s[12:13]
	v_add_u32_e32 v93, 0xe0800, v95
	global_load_dword v128, v93, s[12:13]
	v_add_u32_e32 v93, 0x118a00, v95
	global_load_dword v129, v93, s[12:13]
	v_add_u32_e32 v93, 0x150c00, v95
	global_load_dword v130, v93, s[12:13]
	v_add_u32_e32 v93, 0x188e00, v95
	global_load_dword v131, v93, s[12:13]
	s_add_i32 s34, s34, s25
	s_cmpk_gt_i32 s34, 0x73f
	s_cbranch_scc1 .Lp0w_issued
	s_lshr_b32 s30, s34, 4
	s_and_b32 s6, s34, 15
	s_lshl_b32 s7, s30, 6
	s_mov_b32 s76, 64
	s_cmp_lt_u32 s30, 48
	s_cselect_b32 s77, 0, 16
	s_add_u32 s7, s7, s77
	s_cmp_lt_u32 s30, 0x70
	s_cselect_b32 s7, s7, 0xc00
	s_cselect_b32 s76, s76, 16
	s_cmp_lt_u32 s30, 0x71
	s_cselect_b32 s7, s7, 0
	s_cselect_b32 s76, s76, 0
	s_mul_i32 s77, s6, 0x1c1000
	s_lshl_b32 s7, s7, 2
	s_add_u32 s77, s77, s7
	s_add_u32 s12, s10, s77
	s_addc_u32 s13, s11, 0
	v_cmp_gt_u32_e32 vcc, s76, v72
	s_nop 1
	v_cndmask_b32_e32 v92, 0, v72, vcc
	v_lshl_add_u32 v95, v92, 2, v94
	global_load_dword v132, v95, s[12:13]
	v_add_u32_e32 v93, 0x38200, v95
	global_load_dword v133, v93, s[12:13]
	v_add_u32_e32 v93, 0x70400, v95
	global_load_dword v134, v93, s[12:13]
	v_add_u32_e32 v93, 0xa8600, v95
	global_load_dword v135, v93, s[12:13]
	v_add_u32_e32 v93, 0xe0800, v95
	global_load_dword v136, v93, s[12:13]
	v_add_u32_e32 v93, 0x118a00, v95
	global_load_dword v137, v93, s[12:13]
	v_add_u32_e32 v93, 0x150c00, v95
	global_load_dword v138, v93, s[12:13]
	v_add_u32_e32 v93, 0x188e00, v95
	global_load_dword v139, v93, s[12:13]
	s_add_i32 s34, s34, s25
	s_cmpk_gt_i32 s34, 0x73f
	s_cbranch_scc1 .Lp0w_issued
	s_lshr_b32 s30, s34, 4
	s_and_b32 s6, s34, 15
	s_lshl_b32 s7, s30, 6
	s_mov_b32 s76, 64
	s_cmp_lt_u32 s30, 48
	s_cselect_b32 s77, 0, 16
	s_add_u32 s7, s7, s77
	s_cmp_lt_u32 s30, 0x70
	s_cselect_b32 s7, s7, 0xc00
	s_cselect_b32 s76, s76, 16
	s_cmp_lt_u32 s30, 0x71
	s_cselect_b32 s7, s7, 0
	s_cselect_b32 s76, s76, 0
	s_mul_i32 s77, s6, 0x1c1000
	s_lshl_b32 s7, s7, 2
	s_add_u32 s77, s77, s7
	s_add_u32 s12, s10, s77
	s_addc_u32 s13, s11, 0
	v_cmp_gt_u32_e32 vcc, s76, v72
	s_nop 1
	v_cndmask_b32_e32 v92, 0, v72, vcc
	v_lshl_add_u32 v95, v92, 2, v94
	global_load_dword v140, v95, s[12:13]
	v_add_u32_e32 v93, 0x38200, v95
	global_load_dword v141, v93, s[12:13]
	v_add_u32_e32 v93, 0x70400, v95
	global_load_dword v142, v93, s[12:13]
	v_add_u32_e32 v93, 0xa8600, v95
	global_load_dword v143, v93, s[12:13]
	v_add_u32_e32 v93, 0xe0800, v95
	global_load_dword v144, v93, s[12:13]
	v_add_u32_e32 v93, 0x118a00, v95
	global_load_dword v145, v93, s[12:13]
	v_add_u32_e32 v93, 0x150c00, v95
	global_load_dword v146, v93, s[12:13]
	v_add_u32_e32 v93, 0x188e00, v95
	global_load_dword v147, v93, s[12:13]
	s_add_i32 s34, s34, s25
	s_cmpk_gt_i32 s34, 0x73f
	s_cbranch_scc1 .Lp0w_issued
	s_lshr_b32 s30, s34, 4
	s_and_b32 s6, s34, 15
	s_lshl_b32 s7, s30, 6
	s_mov_b32 s76, 64
	s_cmp_lt_u32 s30, 48
	s_cselect_b32 s77, 0, 16
	s_add_u32 s7, s7, s77
	s_cmp_lt_u32 s30, 0x70
	s_cselect_b32 s7, s7, 0xc00
	s_cselect_b32 s76, s76, 16
	s_cmp_lt_u32 s30, 0x71
	s_cselect_b32 s7, s7, 0
	s_cselect_b32 s76, s76, 0
	s_mul_i32 s77, s6, 0x1c1000
	s_lshl_b32 s7, s7, 2
	s_add_u32 s77, s77, s7
	s_add_u32 s12, s10, s77
	s_addc_u32 s13, s11, 0
	v_cmp_gt_u32_e32 vcc, s76, v72
	s_nop 1
	v_cndmask_b32_e32 v92, 0, v72, vcc
	v_lshl_add_u32 v95, v92, 2, v94
	global_load_dword v148, v95, s[12:13]
	v_add_u32_e32 v93, 0x38200, v95
	global_load_dword v149, v93, s[12:13]
	v_add_u32_e32 v93, 0x70400, v95
	global_load_dword v150, v93, s[12:13]
	v_add_u32_e32 v93, 0xa8600, v95
	global_load_dword v151, v93, s[12:13]
	v_add_u32_e32 v93, 0xe0800, v95
	global_load_dword v152, v93, s[12:13]
	v_add_u32_e32 v93, 0x118a00, v95
	global_load_dword v153, v93, s[12:13]
	v_add_u32_e32 v93, 0x150c00, v95
	global_load_dword v154, v93, s[12:13]
	v_add_u32_e32 v93, 0x188e00, v95
	global_load_dword v155, v93, s[12:13]
	s_add_i32 s34, s34, s25
	s_cmpk_gt_i32 s34, 0x73f
	s_cbranch_scc1 .Lp0w_issued
	s_lshr_b32 s30, s34, 4
	s_and_b32 s6, s34, 15
	s_lshl_b32 s7, s30, 6
	s_mov_b32 s76, 64
	s_cmp_lt_u32 s30, 48
	s_cselect_b32 s77, 0, 16
	s_add_u32 s7, s7, s77
	s_cmp_lt_u32 s30, 0x70
	s_cselect_b32 s7, s7, 0xc00
	s_cselect_b32 s76, s76, 16
	s_cmp_lt_u32 s30, 0x71
	s_cselect_b32 s7, s7, 0
	s_cselect_b32 s76, s76, 0
	s_mul_i32 s77, s6, 0x1c1000
	s_lshl_b32 s7, s7, 2
	s_add_u32 s77, s77, s7
	s_add_u32 s12, s10, s77
	s_addc_u32 s13, s11, 0
	v_cmp_gt_u32_e32 vcc, s76, v72
	s_nop 1
	v_cndmask_b32_e32 v92, 0, v72, vcc
	v_lshl_add_u32 v95, v92, 2, v94
	global_load_dword v156, v95, s[12:13]
	v_add_u32_e32 v93, 0x38200, v95
	global_load_dword v157, v93, s[12:13]
	v_add_u32_e32 v93, 0x70400, v95
	global_load_dword v158, v93, s[12:13]
	v_add_u32_e32 v93, 0xa8600, v95
	global_load_dword v159, v93, s[12:13]
	v_add_u32_e32 v93, 0xe0800, v95
	global_load_dword v160, v93, s[12:13]
	v_add_u32_e32 v93, 0x118a00, v95
	global_load_dword v161, v93, s[12:13]
	v_add_u32_e32 v93, 0x150c00, v95
	global_load_dword v162, v93, s[12:13]
	v_add_u32_e32 v93, 0x188e00, v95
	global_load_dword v163, v93, s[12:13]
	s_add_i32 s34, s34, s25
	s_cmpk_gt_i32 s34, 0x73f
	s_cbranch_scc1 .Lp0w_issued
	s_lshr_b32 s30, s34, 4
	s_and_b32 s6, s34, 15
	s_lshl_b32 s7, s30, 6
	s_mov_b32 s76, 64
	s_cmp_lt_u32 s30, 48
	s_cselect_b32 s77, 0, 16
	s_add_u32 s7, s7, s77
	s_cmp_lt_u32 s30, 0x70
	s_cselect_b32 s7, s7, 0xc00
	s_cselect_b32 s76, s76, 16
	s_cmp_lt_u32 s30, 0x71
	s_cselect_b32 s7, s7, 0
	s_cselect_b32 s76, s76, 0
	s_mul_i32 s77, s6, 0x1c1000
	s_lshl_b32 s7, s7, 2
	s_add_u32 s77, s77, s7
	s_add_u32 s12, s10, s77
	s_addc_u32 s13, s11, 0
	v_cmp_gt_u32_e32 vcc, s76, v72
	s_nop 1
	v_cndmask_b32_e32 v92, 0, v72, vcc
	v_lshl_add_u32 v95, v92, 2, v94
	global_load_dword v164, v95, s[12:13]
	v_add_u32_e32 v93, 0x38200, v95
	global_load_dword v165, v93, s[12:13]
	v_add_u32_e32 v93, 0x70400, v95
	global_load_dword v166, v93, s[12:13]
	v_add_u32_e32 v93, 0xa8600, v95
	global_load_dword v167, v93, s[12:13]
	v_add_u32_e32 v93, 0xe0800, v95
	global_load_dword v168, v93, s[12:13]
	v_add_u32_e32 v93, 0x118a00, v95
	global_load_dword v169, v93, s[12:13]
	v_add_u32_e32 v93, 0x150c00, v95
	global_load_dword v170, v93, s[12:13]
	v_add_u32_e32 v93, 0x188e00, v95
	global_load_dword v171, v93, s[12:13]
	s_add_i32 s34, s34, s25
.Lp0w_issued:
	s_cmpk_gt_i32 s52, 0x73f
	s_cbranch_scc1 .Lp0w_done
	s_lshr_b32 s30, s52, 4
	s_and_b32 s6, s52, 15
	s_lshl_b32 s7, s30, 6
	s_mov_b32 s76, 64
	s_cmp_lt_u32 s30, 48
	s_cselect_b32 s77, 0, 16
	s_add_u32 s7, s7, s77
	s_cmp_lt_u32 s30, 0x70
	s_cselect_b32 s7, s7, 0xc00
	s_cselect_b32 s76, s76, 16
	s_cmp_lt_u32 s30, 0x71
	s_cselect_b32 s7, s7, 0
	s_cselect_b32 s76, s76, 0
	s_waitcnt vmcnt(48)
	v_cmp_gt_u32_e32 vcc, s76, v72
	s_nop 1
	v_cndmask_b32_e32 v108, 0, v108, vcc
	v_cndmask_b32_e32 v109, 0, v109, vcc
	v_cndmask_b32_e32 v110, 0, v110, vcc
	v_cndmask_b32_e32 v111, 0, v111, vcc
	v_cndmask_b32_e32 v112, 0, v112, vcc
	v_cndmask_b32_e32 v113, 0, v113, vcc
	v_cndmask_b32_e32 v114, 0, v114, vcc
	v_cndmask_b32_e32 v115, 0, v115, vcc
	s_lshl_b32 s77, s30, 17
	s_lshl_b32 s7, s6, 7
	s_add_u32 s77, s77, s7
	s_add_u32 s12, s8, s77
	s_addc_u32 s13, s9, 0
	ds_write_b32 v82, v108
	ds_write_b32 v82, v109 offset:2080
	ds_write_b32 v82, v110 offset:4160
	ds_write_b32 v82, v111 offset:6240
	ds_write_b32 v82, v112 offset:8320
	ds_write_b32 v82, v113 offset:10400
	ds_write_b32 v82, v114 offset:12480
	ds_write_b32 v82, v115 offset:14560
	s_waitcnt lgkmcnt(0)
	s_barrier
	ds_read2_b32 v[96:97], v85 offset1:65
	ds_read2_b32 v[98:99], v85 offset0:130 offset1:195
	ds_read2_b32 v[100:101], v89 offset1:65
	ds_read2_b32 v[102:103], v89 offset0:130 offset1:195
	s_waitcnt lgkmcnt(0)
	v_cvt_pk_bf16_f32 v104, v96, v97
	v_cvt_pk_bf16_f32 v105, v98, v99
	v_cvt_pk_bf16_f32 v106, v100, v101
	v_cvt_pk_bf16_f32 v107, v102, v103
	global_store_dwordx4 v91, v[104:107], s[12:13]
	s_add_i32 s52, s52, s25
	s_cmpk_gt_i32 s52, 0x73f
	s_cbranch_scc1 .Lp0w_done
	s_lshr_b32 s30, s52, 4
	s_and_b32 s6, s52, 15
	s_lshl_b32 s7, s30, 6
	s_mov_b32 s76, 64
	s_cmp_lt_u32 s30, 48
	s_cselect_b32 s77, 0, 16
	s_add_u32 s7, s7, s77
	s_cmp_lt_u32 s30, 0x70
	s_cselect_b32 s7, s7, 0xc00
	s_cselect_b32 s76, s76, 16
	s_cmp_lt_u32 s30, 0x71
	s_cselect_b32 s7, s7, 0
	s_cselect_b32 s76, s76, 0
	s_waitcnt vmcnt(41)
	v_cmp_gt_u32_e32 vcc, s76, v72
	s_nop 1
	v_cndmask_b32_e32 v116, 0, v116, vcc
	v_cndmask_b32_e32 v117, 0, v117, vcc
	v_cndmask_b32_e32 v118, 0, v118, vcc
	v_cndmask_b32_e32 v119, 0, v119, vcc
	v_cndmask_b32_e32 v120, 0, v120, vcc
	v_cndmask_b32_e32 v121, 0, v121, vcc
	v_cndmask_b32_e32 v122, 0, v122, vcc
	v_cndmask_b32_e32 v123, 0, v123, vcc
	s_lshl_b32 s77, s30, 17
	s_lshl_b32 s7, s6, 7
	s_add_u32 s77, s77, s7
	s_add_u32 s12, s8, s77
	s_addc_u32 s13, s9, 0
	ds_write_b32 v87, v116
	ds_write_b32 v87, v117 offset:2080
	ds_write_b32 v87, v118 offset:4160
	ds_write_b32 v87, v119 offset:6240
	ds_write_b32 v87, v120 offset:8320
	ds_write_b32 v87, v121 offset:10400
	ds_write_b32 v87, v122 offset:12480
	ds_write_b32 v87, v123 offset:14560
	s_waitcnt lgkmcnt(0)
	s_barrier
	ds_read2_b32 v[96:97], v88 offset1:65
	ds_read2_b32 v[98:99], v88 offset0:130 offset1:195
	ds_read2_b32 v[100:101], v90 offset1:65
	ds_read2_b32 v[102:103], v90 offset0:130 offset1:195
	s_waitcnt lgkmcnt(0)
	v_cvt_pk_bf16_f32 v104, v96, v97
	v_cvt_pk_bf16_f32 v105, v98, v99
	v_cvt_pk_bf16_f32 v106, v100, v101
	v_cvt_pk_bf16_f32 v107, v102, v103
	global_store_dwordx4 v91, v[104:107], s[12:13]
	s_add_i32 s52, s52, s25
	s_cmpk_gt_i32 s52, 0x73f
	s_cbranch_scc1 .Lp0w_done
	s_lshr_b32 s30, s52, 4
	s_and_b32 s6, s52, 15
	s_lshl_b32 s7, s30, 6
	s_mov_b32 s76, 64
	s_cmp_lt_u32 s30, 48
	s_cselect_b32 s77, 0, 16
	s_add_u32 s7, s7, s77
	s_cmp_lt_u32 s30, 0x70
	s_cselect_b32 s7, s7, 0xc00
	s_cselect_b32 s76, s76, 16
	s_cmp_lt_u32 s30, 0x71
	s_cselect_b32 s7, s7, 0
	s_cselect_b32 s76, s76, 0
	s_waitcnt vmcnt(34)
	v_cmp_gt_u32_e32 vcc, s76, v72
	s_nop 1
	v_cndmask_b32_e32 v124, 0, v124, vcc
	v_cndmask_b32_e32 v125, 0, v125, vcc
	v_cndmask_b32_e32 v126, 0, v126, vcc
	v_cndmask_b32_e32 v127, 0, v127, vcc
	v_cndmask_b32_e32 v128, 0, v128, vcc
	v_cndmask_b32_e32 v129, 0, v129, vcc
	v_cndmask_b32_e32 v130, 0, v130, vcc
	v_cndmask_b32_e32 v131, 0, v131, vcc
	s_lshl_b32 s77, s30, 17
	s_lshl_b32 s7, s6, 7
	s_add_u32 s77, s77, s7
	s_add_u32 s12, s8, s77
	s_addc_u32 s13, s9, 0
	ds_write_b32 v82, v124
	ds_write_b32 v82, v125 offset:2080
	ds_write_b32 v82, v126 offset:4160
	ds_write_b32 v82, v127 offset:6240
	ds_write_b32 v82, v128 offset:8320
	ds_write_b32 v82, v129 offset:10400
	ds_write_b32 v82, v130 offset:12480
	ds_write_b32 v82, v131 offset:14560
	s_waitcnt lgkmcnt(0)
	s_barrier
	ds_read2_b32 v[96:97], v85 offset1:65
	ds_read2_b32 v[98:99], v85 offset0:130 offset1:195
	ds_read2_b32 v[100:101], v89 offset1:65
	ds_read2_b32 v[102:103], v89 offset0:130 offset1:195
	s_waitcnt lgkmcnt(0)
	v_cvt_pk_bf16_f32 v104, v96, v97
	v_cvt_pk_bf16_f32 v105, v98, v99
	v_cvt_pk_bf16_f32 v106, v100, v101
	v_cvt_pk_bf16_f32 v107, v102, v103
	global_store_dwordx4 v91, v[104:107], s[12:13]
	s_add_i32 s52, s52, s25
	s_cmpk_gt_i32 s52, 0x73f
	s_cbranch_scc1 .Lp0w_done
	s_lshr_b32 s30, s52, 4
	s_and_b32 s6, s52, 15
	s_lshl_b32 s7, s30, 6
	s_mov_b32 s76, 64
	s_cmp_lt_u32 s30, 48
	s_cselect_b32 s77, 0, 16
	s_add_u32 s7, s7, s77
	s_cmp_lt_u32 s30, 0x70
	s_cselect_b32 s7, s7, 0xc00
	s_cselect_b32 s76, s76, 16
	s_cmp_lt_u32 s30, 0x71
	s_cselect_b32 s7, s7, 0
	s_cselect_b32 s76, s76, 0
	s_waitcnt vmcnt(27)
	v_cmp_gt_u32_e32 vcc, s76, v72
	s_nop 1
	v_cndmask_b32_e32 v132, 0, v132, vcc
	v_cndmask_b32_e32 v133, 0, v133, vcc
	v_cndmask_b32_e32 v134, 0, v134, vcc
	v_cndmask_b32_e32 v135, 0, v135, vcc
	v_cndmask_b32_e32 v136, 0, v136, vcc
	v_cndmask_b32_e32 v137, 0, v137, vcc
	v_cndmask_b32_e32 v138, 0, v138, vcc
	v_cndmask_b32_e32 v139, 0, v139, vcc
	s_lshl_b32 s77, s30, 17
	s_lshl_b32 s7, s6, 7
	s_add_u32 s77, s77, s7
	s_add_u32 s12, s8, s77
	s_addc_u32 s13, s9, 0
	ds_write_b32 v87, v132
	ds_write_b32 v87, v133 offset:2080
	ds_write_b32 v87, v134 offset:4160
	ds_write_b32 v87, v135 offset:6240
	ds_write_b32 v87, v136 offset:8320
	ds_write_b32 v87, v137 offset:10400
	ds_write_b32 v87, v138 offset:12480
	ds_write_b32 v87, v139 offset:14560
	s_waitcnt lgkmcnt(0)
	s_barrier
	ds_read2_b32 v[96:97], v88 offset1:65
	ds_read2_b32 v[98:99], v88 offset0:130 offset1:195
	ds_read2_b32 v[100:101], v90 offset1:65
	ds_read2_b32 v[102:103], v90 offset0:130 offset1:195
	s_waitcnt lgkmcnt(0)
	v_cvt_pk_bf16_f32 v104, v96, v97
	v_cvt_pk_bf16_f32 v105, v98, v99
	v_cvt_pk_bf16_f32 v106, v100, v101
	v_cvt_pk_bf16_f32 v107, v102, v103
	global_store_dwordx4 v91, v[104:107], s[12:13]
	s_add_i32 s52, s52, s25
	s_cmpk_gt_i32 s52, 0x73f
	s_cbranch_scc1 .Lp0w_done
	s_lshr_b32 s30, s52, 4
	s_and_b32 s6, s52, 15
	s_lshl_b32 s7, s30, 6
	s_mov_b32 s76, 64
	s_cmp_lt_u32 s30, 48
	s_cselect_b32 s77, 0, 16
	s_add_u32 s7, s7, s77
	s_cmp_lt_u32 s30, 0x70
	s_cselect_b32 s7, s7, 0xc00
	s_cselect_b32 s76, s76, 16
	s_cmp_lt_u32 s30, 0x71
	s_cselect_b32 s7, s7, 0
	s_cselect_b32 s76, s76, 0
	s_waitcnt vmcnt(20)
	v_cmp_gt_u32_e32 vcc, s76, v72
	s_nop 1
	v_cndmask_b32_e32 v140, 0, v140, vcc
	v_cndmask_b32_e32 v141, 0, v141, vcc
	v_cndmask_b32_e32 v142, 0, v142, vcc
	v_cndmask_b32_e32 v143, 0, v143, vcc
	v_cndmask_b32_e32 v144, 0, v144, vcc
	v_cndmask_b32_e32 v145, 0, v145, vcc
	v_cndmask_b32_e32 v146, 0, v146, vcc
	v_cndmask_b32_e32 v147, 0, v147, vcc
	s_lshl_b32 s77, s30, 17
	s_lshl_b32 s7, s6, 7
	s_add_u32 s77, s77, s7
	s_add_u32 s12, s8, s77
	s_addc_u32 s13, s9, 0
	ds_write_b32 v82, v140
	ds_write_b32 v82, v141 offset:2080
	ds_write_b32 v82, v142 offset:4160
	ds_write_b32 v82, v143 offset:6240
	ds_write_b32 v82, v144 offset:8320
	ds_write_b32 v82, v145 offset:10400
	ds_write_b32 v82, v146 offset:12480
	ds_write_b32 v82, v147 offset:14560
	s_waitcnt lgkmcnt(0)
	s_barrier
	ds_read2_b32 v[96:97], v85 offset1:65
	ds_read2_b32 v[98:99], v85 offset0:130 offset1:195
	ds_read2_b32 v[100:101], v89 offset1:65
	ds_read2_b32 v[102:103], v89 offset0:130 offset1:195
	s_waitcnt lgkmcnt(0)
	v_cvt_pk_bf16_f32 v104, v96, v97
	v_cvt_pk_bf16_f32 v105, v98, v99
	v_cvt_pk_bf16_f32 v106, v100, v101
	v_cvt_pk_bf16_f32 v107, v102, v103
	global_store_dwordx4 v91, v[104:107], s[12:13]
	s_add_i32 s52, s52, s25
	s_cmpk_gt_i32 s52, 0x73f
	s_cbranch_scc1 .Lp0w_done
	s_lshr_b32 s30, s52, 4
	s_and_b32 s6, s52, 15
	s_lshl_b32 s7, s30, 6
	s_mov_b32 s76, 64
	s_cmp_lt_u32 s30, 48
	s_cselect_b32 s77, 0, 16
	s_add_u32 s7, s7, s77
	s_cmp_lt_u32 s30, 0x70
	s_cselect_b32 s7, s7, 0xc00
	s_cselect_b32 s76, s76, 16
	s_cmp_lt_u32 s30, 0x71
	s_cselect_b32 s7, s7, 0
	s_cselect_b32 s76, s76, 0
	s_waitcnt vmcnt(13)
	v_cmp_gt_u32_e32 vcc, s76, v72
	s_nop 1
	v_cndmask_b32_e32 v148, 0, v148, vcc
	v_cndmask_b32_e32 v149, 0, v149, vcc
	v_cndmask_b32_e32 v150, 0, v150, vcc
	v_cndmask_b32_e32 v151, 0, v151, vcc
	v_cndmask_b32_e32 v152, 0, v152, vcc
	v_cndmask_b32_e32 v153, 0, v153, vcc
	v_cndmask_b32_e32 v154, 0, v154, vcc
	v_cndmask_b32_e32 v155, 0, v155, vcc
	s_lshl_b32 s77, s30, 17
	s_lshl_b32 s7, s6, 7
	s_add_u32 s77, s77, s7
	s_add_u32 s12, s8, s77
	s_addc_u32 s13, s9, 0
	ds_write_b32 v87, v148
	ds_write_b32 v87, v149 offset:2080
	ds_write_b32 v87, v150 offset:4160
	ds_write_b32 v87, v151 offset:6240
	ds_write_b32 v87, v152 offset:8320
	ds_write_b32 v87, v153 offset:10400
	ds_write_b32 v87, v154 offset:12480
	ds_write_b32 v87, v155 offset:14560
	s_waitcnt lgkmcnt(0)
	s_barrier
	ds_read2_b32 v[96:97], v88 offset1:65
	ds_read2_b32 v[98:99], v88 offset0:130 offset1:195
	ds_read2_b32 v[100:101], v90 offset1:65
	ds_read2_b32 v[102:103], v90 offset0:130 offset1:195
	s_waitcnt lgkmcnt(0)
	v_cvt_pk_bf16_f32 v104, v96, v97
	v_cvt_pk_bf16_f32 v105, v98, v99
	v_cvt_pk_bf16_f32 v106, v100, v101
	v_cvt_pk_bf16_f32 v107, v102, v103
	global_store_dwordx4 v91, v[104:107], s[12:13]
	s_add_i32 s52, s52, s25
	s_cmpk_gt_i32 s52, 0x73f
	s_cbranch_scc1 .Lp0w_done
	s_lshr_b32 s30, s52, 4
	s_and_b32 s6, s52, 15
	s_lshl_b32 s7, s30, 6
	s_mov_b32 s76, 64
	s_cmp_lt_u32 s30, 48
	s_cselect_b32 s77, 0, 16
	s_add_u32 s7, s7, s77
	s_cmp_lt_u32 s30, 0x70
	s_cselect_b32 s7, s7, 0xc00
	s_cselect_b32 s76, s76, 16
	s_cmp_lt_u32 s30, 0x71
	s_cselect_b32 s7, s7, 0
	s_cselect_b32 s76, s76, 0
	s_waitcnt vmcnt(6)
	v_cmp_gt_u32_e32 vcc, s76, v72
	s_nop 1
	v_cndmask_b32_e32 v156, 0, v156, vcc
	v_cndmask_b32_e32 v157, 0, v157, vcc
	v_cndmask_b32_e32 v158, 0, v158, vcc
	v_cndmask_b32_e32 v159, 0, v159, vcc
	v_cndmask_b32_e32 v160, 0, v160, vcc
	v_cndmask_b32_e32 v161, 0, v161, vcc
	v_cndmask_b32_e32 v162, 0, v162, vcc
	v_cndmask_b32_e32 v163, 0, v163, vcc
	s_lshl_b32 s77, s30, 17
	s_lshl_b32 s7, s6, 7
	s_add_u32 s77, s77, s7
	s_add_u32 s12, s8, s77
	s_addc_u32 s13, s9, 0
	ds_write_b32 v82, v156
	ds_write_b32 v82, v157 offset:2080
	ds_write_b32 v82, v158 offset:4160
	ds_write_b32 v82, v159 offset:6240
	ds_write_b32 v82, v160 offset:8320
	ds_write_b32 v82, v161 offset:10400
	ds_write_b32 v82, v162 offset:12480
	ds_write_b32 v82, v163 offset:14560
	s_waitcnt lgkmcnt(0)
	s_barrier
	ds_read2_b32 v[96:97], v85 offset1:65
	ds_read2_b32 v[98:99], v85 offset0:130 offset1:195
	ds_read2_b32 v[100:101], v89 offset1:65
	ds_read2_b32 v[102:103], v89 offset0:130 offset1:195
	s_waitcnt lgkmcnt(0)
	v_cvt_pk_bf16_f32 v104, v96, v97
	v_cvt_pk_bf16_f32 v105, v98, v99
	v_cvt_pk_bf16_f32 v106, v100, v101
	v_cvt_pk_bf16_f32 v107, v102, v103
	global_store_dwordx4 v91, v[104:107], s[12:13]
	s_add_i32 s52, s52, s25
	s_cmpk_gt_i32 s52, 0x73f
	s_cbranch_scc1 .Lp0w_done
	s_lshr_b32 s30, s52, 4
	s_and_b32 s6, s52, 15
	s_lshl_b32 s7, s30, 6
	s_mov_b32 s76, 64
	s_cmp_lt_u32 s30, 48
	s_cselect_b32 s77, 0, 16
	s_add_u32 s7, s7, s77
	s_cmp_lt_u32 s30, 0x70
	s_cselect_b32 s7, s7, 0xc00
	s_cselect_b32 s76, s76, 16
	s_cmp_lt_u32 s30, 0x71
	s_cselect_b32 s7, s7, 0
	s_cselect_b32 s76, s76, 0
	s_waitcnt vmcnt(7)
	v_cmp_gt_u32_e32 vcc, s76, v72
	s_nop 1
	v_cndmask_b32_e32 v164, 0, v164, vcc
	v_cndmask_b32_e32 v165, 0, v165, vcc
	v_cndmask_b32_e32 v166, 0, v166, vcc
	v_cndmask_b32_e32 v167, 0, v167, vcc
	v_cndmask_b32_e32 v168, 0, v168, vcc
	v_cndmask_b32_e32 v169, 0, v169, vcc
	v_cndmask_b32_e32 v170, 0, v170, vcc
	v_cndmask_b32_e32 v171, 0, v171, vcc
	s_lshl_b32 s77, s30, 17
	s_lshl_b32 s7, s6, 7
	s_add_u32 s77, s77, s7
	s_add_u32 s12, s8, s77
	s_addc_u32 s13, s9, 0
	ds_write_b32 v87, v164
	ds_write_b32 v87, v165 offset:2080
	ds_write_b32 v87, v166 offset:4160
	ds_write_b32 v87, v167 offset:6240
	ds_write_b32 v87, v168 offset:8320
	ds_write_b32 v87, v169 offset:10400
	ds_write_b32 v87, v170 offset:12480
	ds_write_b32 v87, v171 offset:14560
	s_waitcnt lgkmcnt(0)
	s_barrier
	ds_read2_b32 v[96:97], v88 offset1:65
	ds_read2_b32 v[98:99], v88 offset0:130 offset1:195
	ds_read2_b32 v[100:101], v90 offset1:65
	ds_read2_b32 v[102:103], v90 offset0:130 offset1:195
	s_waitcnt lgkmcnt(0)
	v_cvt_pk_bf16_f32 v104, v96, v97
	v_cvt_pk_bf16_f32 v105, v98, v99
	v_cvt_pk_bf16_f32 v106, v100, v101
	v_cvt_pk_bf16_f32 v107, v102, v103
	global_store_dwordx4 v91, v[104:107], s[12:13]
	s_add_i32 s52, s52, s25
.Lp0w_done:
	s_barrier
	s_lshl_b32 s68, s52, 6
	s_branch .LBB0_628

.LBB0_636:
	s_andn2_b64 vcc, exec, s[6:7]
	s_cbranch_vccnz .LBB0_654
	s_cmp_lg_u32 s25, 0x100
	s_cbranch_scc1 .Lp0u_orig
	s_load_dwordx4 s[76:79], s[0:1], 0xa0
	v_and_b32_e32 v72, 63, v208
	v_lshrrev_b32_e32 v73, 6, v208
	v_mul_u32_u24_e32 v82, 65, v73
	v_add_lshl_u32 v82, v82, v72, 2
	v_lshrrev_b32_e32 v83, 3, v208
	v_and_b32_e32 v84, 7, v208
	v_lshlrev_b32_e32 v84, 3, v84
	v_mul_u32_u24_e32 v85, 0x104, v84
	v_lshl_add_u32 v85, v83, 2, v85
	v_add_u32_e32 v87, 0x4200, v82
	v_add_u32_e32 v88, 0x4200, v85
	v_add_u32_e32 v89, 0x410, v85
	v_add_u32_e32 v90, 0x410, v88
	v_lshlrev_b32_e32 v91, 11, v83
	v_lshl_add_u32 v91, v84, 1, v91
	v_lshlrev_b32_e32 v94, 14, v73
	v_lshl_add_u32 v94, v72, 2, v94
	v_lshlrev_b32_e32 v92, 2, v73
	v_add_u32_e32 v173, 0x20000, v94
	v_add_u32_e32 v174, 0x40000, v94
	v_add_u32_e32 v175, 0x60000, v94
	v_add_u32_e32 v176, 0x80000, v94
	v_add_u32_e32 v177, 0xa0000, v94
	v_add_u32_e32 v178, 0xc0000, v94
	v_add_u32_e32 v179, 0xe0000, v94
	s_waitcnt lgkmcnt(0)
	s_mov_b32 s34, s52
	s_add_i32 s30, s34, 0xfffff5c0
	s_lshr_b32 s30, s30, 4
	s_and_b32 s6, s34, 15
	s_lshl_b32 s7, s6, 20
	s_lshl_b32 s30, s30, 8
	s_add_u32 s7, s7, s30
	s_add_u32 s12, s78, s7
	s_addc_u32 s13, s79, 0
	s_lshl_b32 s7, s6, 8
	s_add_u32 s10, s76, s7
	s_addc_u32 s11, s77, 0
	global_load_dword v108, v94, s[12:13]
	global_load_dword v109, v173, s[12:13]
	global_load_dword v110, v174, s[12:13]
	global_load_dword v111, v175, s[12:13]
	global_load_dword v112, v176, s[12:13]
	global_load_dword v113, v177, s[12:13]
	global_load_dword v114, v178, s[12:13]
	global_load_dword v115, v179, s[12:13]
	global_load_dword v116, v92, s[10:11]
	global_load_dword v117, v92, s[10:11] offset:32
	global_load_dword v118, v92, s[10:11] offset:64
	global_load_dword v119, v92, s[10:11] offset:96
	global_load_dword v120, v92, s[10:11] offset:128
	global_load_dword v121, v92, s[10:11] offset:160
	global_load_dword v122, v92, s[10:11] offset:192
	global_load_dword v123, v92, s[10:11] offset:224
	s_add_i32 s34, s34, s25
	s_add_i32 s30, s34, 0xfffff5c0
	s_lshr_b32 s30, s30, 4
	s_and_b32 s6, s34, 15
	s_lshl_b32 s7, s6, 20
	s_lshl_b32 s30, s30, 8
	s_add_u32 s7, s7, s30
	s_add_u32 s12, s78, s7
	s_addc_u32 s13, s79, 0
	s_lshl_b32 s7, s6, 8
	s_add_u32 s10, s76, s7
	s_addc_u32 s11, s77, 0
	global_load_dword v124, v94, s[12:13]
	global_load_dword v125, v173, s[12:13]
	global_load_dword v126, v174, s[12:13]
	global_load_dword v127, v175, s[12:13]
	global_load_dword v128, v176, s[12:13]
	global_load_dword v129, v177, s[12:13]
	global_load_dword v130, v178, s[12:13]
	global_load_dword v131, v179, s[12:13]
	global_load_dword v132, v92, s[10:11]
	global_load_dword v133, v92, s[10:11] offset:32
	global_load_dword v134, v92, s[10:11] offset:64
	global_load_dword v135, v92, s[10:11] offset:96
	global_load_dword v136, v92, s[10:11] offset:128
	global_load_dword v137, v92, s[10:11] offset:160
	global_load_dword v138, v92, s[10:11] offset:192
	global_load_dword v139, v92, s[10:11] offset:224
	s_add_i32 s34, s34, s25
	s_add_i32 s30, s34, 0xfffff5c0
	s_lshr_b32 s30, s30, 4
	s_and_b32 s6, s34, 15
	s_lshl_b32 s7, s6, 20
	s_lshl_b32 s30, s30, 8
	s_add_u32 s7, s7, s30
	s_add_u32 s12, s78, s7
	s_addc_u32 s13, s79, 0
	s_lshl_b32 s7, s6, 8
	s_add_u32 s10, s76, s7
	s_addc_u32 s11, s77, 0
	global_load_dword v140, v94, s[12:13]
	global_load_dword v141, v173, s[12:13]
	global_load_dword v142, v174, s[12:13]
	global_load_dword v143, v175, s[12:13]
	global_load_dword v144, v176, s[12:13]
	global_load_dword v145, v177, s[12:13]
	global_load_dword v146, v178, s[12:13]
	global_load_dword v147, v179, s[12:13]
	global_load_dword v148, v92, s[10:11]
	global_load_dword v149, v92, s[10:11] offset:32
	global_load_dword v150, v92, s[10:11] offset:64
	global_load_dword v151, v92, s[10:11] offset:96
	global_load_dword v152, v92, s[10:11] offset:128
	global_load_dword v153, v92, s[10:11] offset:160
	global_load_dword v154, v92, s[10:11] offset:192
	global_load_dword v155, v92, s[10:11] offset:224
	s_add_i32 s34, s34, s25
	s_add_i32 s30, s34, 0xfffff5c0
	s_lshr_b32 s30, s30, 4
	s_and_b32 s6, s34, 15
	s_lshl_b32 s7, s6, 20
	s_lshl_b32 s30, s30, 8
	s_add_u32 s7, s7, s30
	s_add_u32 s12, s78, s7
	s_addc_u32 s13, s79, 0
	s_lshl_b32 s7, s6, 8
	s_add_u32 s10, s76, s7
	s_addc_u32 s11, s77, 0
	global_load_dword v156, v94, s[12:13]
	global_load_dword v157, v173, s[12:13]
	global_load_dword v158, v174, s[12:13]
	global_load_dword v159, v175, s[12:13]
	global_load_dword v160, v176, s[12:13]
	global_load_dword v161, v177, s[12:13]
	global_load_dword v162, v178, s[12:13]
	global_load_dword v163, v179, s[12:13]
	global_load_dword v164, v92, s[10:11]
	global_load_dword v165, v92, s[10:11] offset:32
	global_load_dword v166, v92, s[10:11] offset:64
	global_load_dword v167, v92, s[10:11] offset:96
	global_load_dword v168, v92, s[10:11] offset:128
	global_load_dword v169, v92, s[10:11] offset:160
	global_load_dword v170, v92, s[10:11] offset:192
	global_load_dword v171, v92, s[10:11] offset:224
	s_add_i32 s34, s34, s25
	s_waitcnt vmcnt(48)
	v_mul_f32_e32 v108, v108, v116
	v_mul_f32_e32 v109, v109, v117
	v_mul_f32_e32 v110, v110, v118
	v_mul_f32_e32 v111, v111, v119
	v_mul_f32_e32 v112, v112, v120
	v_mul_f32_e32 v113, v113, v121
	v_mul_f32_e32 v114, v114, v122
	v_mul_f32_e32 v115, v115, v123
	s_add_i32 s30, s52, 0xfffff5c0
	s_lshr_b32 s30, s30, 4
	s_and_b32 s6, s52, 15
	s_lshl_b32 s30, s30, 17
	s_lshl_b32 s7, s6, 7
	s_add_u32 s30, s30, s7
	s_add_u32 s12, s22, s30
	s_addc_u32 s13, s23, 0
	ds_write_b32 v82, v108
	ds_write_b32 v82, v109 offset:2080
	ds_write_b32 v82, v110 offset:4160
	ds_write_b32 v82, v111 offset:6240
	ds_write_b32 v82, v112 offset:8320
	ds_write_b32 v82, v113 offset:10400
	ds_write_b32 v82, v114 offset:12480
	ds_write_b32 v82, v115 offset:14560
	s_waitcnt lgkmcnt(0)
	s_barrier
	ds_read2_b32 v[96:97], v85 offset1:65
	ds_read2_b32 v[98:99], v85 offset0:130 offset1:195
	ds_read2_b32 v[100:101], v89 offset1:65
	ds_read2_b32 v[102:103], v89 offset0:130 offset1:195
	s_waitcnt lgkmcnt(0)
	v_cvt_pk_bf16_f32 v104, v96, v97
	v_cvt_pk_bf16_f32 v105, v98, v99
	v_cvt_pk_bf16_f32 v106, v100, v101
	v_cvt_pk_bf16_f32 v107, v102, v103
	global_store_dwordx4 v91, v[104:107], s[12:13]
	s_add_i32 s52, s52, s25
	s_waitcnt vmcnt(33)
	v_mul_f32_e32 v124, v124, v132
	v_mul_f32_e32 v125, v125, v133
	v_mul_f32_e32 v126, v126, v134
	v_mul_f32_e32 v127, v127, v135
	v_mul_f32_e32 v128, v128, v136
	v_mul_f32_e32 v129, v129, v137
	v_mul_f32_e32 v130, v130, v138
	v_mul_f32_e32 v131, v131, v139
	s_add_i32 s30, s52, 0xfffff5c0
	s_lshr_b32 s30, s30, 4
	s_and_b32 s6, s52, 15
	s_lshl_b32 s30, s30, 17
	s_lshl_b32 s7, s6, 7
	s_add_u32 s30, s30, s7
	s_add_u32 s12, s22, s30
	s_addc_u32 s13, s23, 0
	ds_write_b32 v87, v124
	ds_write_b32 v87, v125 offset:2080
	ds_write_b32 v87, v126 offset:4160
	ds_write_b32 v87, v127 offset:6240
	ds_write_b32 v87, v128 offset:8320
	ds_write_b32 v87, v129 offset:10400
	ds_write_b32 v87, v130 offset:12480
	ds_write_b32 v87, v131 offset:14560
	s_waitcnt lgkmcnt(0)
	s_barrier
	ds_read2_b32 v[96:97], v88 offset1:65
	ds_read2_b32 v[98:99], v88 offset0:130 offset1:195
	ds_read2_b32 v[100:101], v90 offset1:65
	ds_read2_b32 v[102:103], v90 offset0:130 offset1:195
	s_waitcnt lgkmcnt(0)
	v_cvt_pk_bf16_f32 v104, v96, v97
	v_cvt_pk_bf16_f32 v105, v98, v99
	v_cvt_pk_bf16_f32 v106, v100, v101
	v_cvt_pk_bf16_f32 v107, v102, v103
	global_store_dwordx4 v91, v[104:107], s[12:13]
	s_add_i32 s52, s52, s25
	s_waitcnt vmcnt(18)
	v_mul_f32_e32 v140, v140, v148
	v_mul_f32_e32 v141, v141, v149
	v_mul_f32_e32 v142, v142, v150
	v_mul_f32_e32 v143, v143, v151
	v_mul_f32_e32 v144, v144, v152
	v_mul_f32_e32 v145, v145, v153
	v_mul_f32_e32 v146, v146, v154
	v_mul_f32_e32 v147, v147, v155
	s_add_i32 s30, s52, 0xfffff5c0
	s_lshr_b32 s30, s30, 4
	s_and_b32 s6, s52, 15
	s_lshl_b32 s30, s30, 17
	s_lshl_b32 s7, s6, 7
	s_add_u32 s30, s30, s7
	s_add_u32 s12, s22, s30
	s_addc_u32 s13, s23, 0
	ds_write_b32 v82, v140
	ds_write_b32 v82, v141 offset:2080
	ds_write_b32 v82, v142 offset:4160
	ds_write_b32 v82, v143 offset:6240
	ds_write_b32 v82, v144 offset:8320
	ds_write_b32 v82, v145 offset:10400
	ds_write_b32 v82, v146 offset:12480
	ds_write_b32 v82, v147 offset:14560
	s_waitcnt lgkmcnt(0)
	s_barrier
	ds_read2_b32 v[96:97], v85 offset1:65
	ds_read2_b32 v[98:99], v85 offset0:130 offset1:195
	ds_read2_b32 v[100:101], v89 offset1:65
	ds_read2_b32 v[102:103], v89 offset0:130 offset1:195
	s_waitcnt lgkmcnt(0)
	v_cvt_pk_bf16_f32 v104, v96, v97
	v_cvt_pk_bf16_f32 v105, v98, v99
	v_cvt_pk_bf16_f32 v106, v100, v101
	v_cvt_pk_bf16_f32 v107, v102, v103
	global_store_dwordx4 v91, v[104:107], s[12:13]
	s_add_i32 s52, s52, s25
	s_waitcnt vmcnt(3)
	v_mul_f32_e32 v156, v156, v164
	v_mul_f32_e32 v157, v157, v165
	v_mul_f32_e32 v158, v158, v166
	v_mul_f32_e32 v159, v159, v167
	v_mul_f32_e32 v160, v160, v168
	v_mul_f32_e32 v161, v161, v169
	v_mul_f32_e32 v162, v162, v170
	v_mul_f32_e32 v163, v163, v171
	s_add_i32 s30, s52, 0xfffff5c0
	s_lshr_b32 s30, s30, 4
	s_and_b32 s6, s52, 15
	s_lshl_b32 s30, s30, 17
	s_lshl_b32 s7, s6, 7
	s_add_u32 s30, s30, s7
	s_add_u32 s12, s22, s30
	s_addc_u32 s13, s23, 0
	ds_write_b32 v87, v156
	ds_write_b32 v87, v157 offset:2080
	ds_write_b32 v87, v158 offset:4160
	ds_write_b32 v87, v159 offset:6240
	ds_write_b32 v87, v160 offset:8320
	ds_write_b32 v87, v161 offset:10400
	ds_write_b32 v87, v162 offset:12480
	ds_write_b32 v87, v163 offset:14560
	s_waitcnt lgkmcnt(0)
	s_barrier
	ds_read2_b32 v[96:97], v88 offset1:65
	ds_read2_b32 v[98:99], v88 offset0:130 offset1:195
	ds_read2_b32 v[100:101], v90 offset1:65
	ds_read2_b32 v[102:103], v90 offset0:130 offset1:195
	s_waitcnt lgkmcnt(0)
	v_cvt_pk_bf16_f32 v104, v96, v97
	v_cvt_pk_bf16_f32 v105, v98, v99
	v_cvt_pk_bf16_f32 v106, v100, v101
	v_cvt_pk_bf16_f32 v107, v102, v103
	global_store_dwordx4 v91, v[104:107], s[12:13]
	s_add_i32 s52, s52, s25
	s_barrier
	s_lshl_b32 s68, s52, 6
	s_branch .LBB0_628
.Lp0u_orig:
	s_load_dwordx4 s[76:79], s[0:1], 0xa0
	s_add_i32 s6, s52, 0xfffff5c0
	s_and_b32 s12, s52, 15
	s_lshr_b32 s30, s6, 4
	s_lshl_b32 s6, s12, 20
	v_mov_b32_e32 v1, v208
	s_waitcnt lgkmcnt(0)
	s_add_u32 s6, s78, s6
	s_addc_u32 s7, s79, 0
	s_waitcnt vmcnt(0)
	v_ashrrev_i32_e32 v8, 6, v1
	v_lshl_or_b32 v4, s30, 6, v2
	v_mov_b32_e32 v5, v0
	v_ashrrev_i32_e32 v9, 31, v8
	v_lshl_add_u64 v[4:5], v[4:5], 2, s[6:7]
	v_lshlrev_b64 v[6:7], 14, v[8:9]
	v_lshl_add_u64 v[4:5], v[4:5], 0, v[6:7]
	global_load_dword v10, v[4:5], off
	s_lshl_b32 s6, s12, 8
	s_add_u32 s6, s76, s6
	s_addc_u32 s7, s77, 0
	s_cmp_lg_u64 s[76:77], 0
	s_cselect_b64 s[10:11], -1, 0
	s_cmp_eq_u64 s[76:77], 0
	v_lshl_add_u64 v[6:7], v[8:9], 2, s[6:7]
	s_cbranch_scc1 .LBB0_639
	global_load_dword v3, v[6:7], off
	s_waitcnt vmcnt(0)
	v_mul_f32_e32 v10, v10, v3
